# v118 with the P5 gate loads of the second gate issued only in the pass that needs them (no extra gate traffic in the final pass); counted waits adjusted
# speedup vs baseline: 1.0087x; 1.0087x over previous
.LBB0_845:
	v_mov_b32_e32 v142, v165
	v_mov_b32_e32 v143, v150
	v_mov_b32_e32 v144, v1
	v_mov_b32_e32 v145, v151
	s_lshl_b32 s4, s33, 8
	s_lshl_b32 s2, s2, 8
	s_add_i32 s4, s4, s30
	v_add_u32_e32 v144, s4, v143
	s_or_b32 s2, s2, s31
	v_lshl_add_u32 v142, v145, 3, s2
	v_ashrrev_i32_e32 v145, 31, v144
	v_lshlrev_b64 v[146:147], 13, v[144:145]
	v_lshl_add_u64 v[146:147], s[70:71], 0, v[146:147]
	v_ashrrev_i32_e32 v143, 31, v142
	v_lshl_add_u64 v[146:147], v[142:143], 1, v[146:147]
	v_lshl_add_u64 v[188:189], v[146:147], 0, s[12:13]
	global_load_dwordx4 v[172:175], v[188:189], off
	global_load_dwordx4 v[180:183], v[188:189], off offset:256
	s_cmp_lg_u32 s44, 3
	s_cbranch_scc1 .Lp5_noga_0
	global_load_dwordx4 v[176:179], v[146:147], off
	global_load_dwordx4 v[184:187], v[146:147], off offset:256
.Lp5_noga_0:
	v_add_co_u32_e32 v148, vcc, s38, v146
	s_cmp_lg_u32 s44, 3
	s_nop 0
	v_addc_co_u32_e32 v149, vcc, 0, v147, vcc
	v_lshlrev_b64 v[148:149], 12, v[144:145]
	s_cselect_b64 s[20:21], -1, 0
	v_lshl_add_u64 v[148:149], s[82:83], 0, v[148:149]
	s_mov_b64 s[4:5], -1
	s_and_b64 vcc, exec, s[20:21]
	v_lshl_add_u64 v[148:149], v[142:143], 1, v[148:149]
	s_waitcnt vmcnt(1)
	v_lshlrev_b32_e32 v159, 16, v172
	v_and_b32_e32 v158, 0xffff0000, v172
	v_lshlrev_b32_e32 v155, 16, v173
	v_and_b32_e32 v154, 0xffff0000, v173
	v_lshlrev_b32_e32 v160, 16, v174
	v_and_b32_e32 v157, 0xffff0000, v174
	v_lshlrev_b32_e32 v156, 16, v175
	v_and_b32_e32 v145, 0xffff0000, v175
	s_cbranch_vccz .LBB0_847
	v_mul_f32_e32 v161, v126, v159
	v_mul_f32_e32 v162, v127, v158
	v_cvt_pk_bf16_f32 v166, v161, v162
	v_mul_f32_e32 v161, v128, v155
	v_mul_f32_e32 v162, v129, v154
	v_cvt_pk_bf16_f32 v167, v161, v162
	v_mul_f32_e32 v161, v122, v160
	v_mul_f32_e32 v162, v123, v157
	v_cvt_pk_bf16_f32 v168, v161, v162
	v_mul_f32_e32 v161, v124, v156
	v_mul_f32_e32 v162, v125, v145
	v_cvt_pk_bf16_f32 v169, v161, v162
	global_store_dwordx4 v[148:149], v[166:169], off
	s_mov_b64 s[4:5], 0
.LBB0_847:
	s_andn2_b64 vcc, exec, s[4:5]
	s_cbranch_vccnz .LBB0_849
	v_max_f32_e32 v159, v159, v159
	v_max_f32_e32 v160, v160, v160
	v_max_f32_e32 v158, v158, v158
	v_max_f32_e32 v157, v157, v157
	v_max_f32_e32 v155, v155, v155
	v_max_f32_e32 v156, v156, v156
	v_max_f32_e32 v154, v154, v154
	v_max_f32_e32 v145, v145, v145
	v_max_f32_e32 v159, 0xda24260, v159
	v_max_f32_e32 v160, 0xda24260, v160
	v_max_f32_e32 v158, 0xda24260, v158
	v_max_f32_e32 v157, 0xda24260, v157
	v_max_f32_e32 v161, 0xda24260, v155
	v_max_f32_e32 v162, 0xda24260, v156
	v_max_f32_e32 v163, 0xda24260, v154
	v_max_f32_e32 v145, 0xda24260, v145
	v_rcp_f32_e32 v154, v159
	v_rcp_f32_e32 v156, v160
	v_rcp_f32_e32 v155, v158
	v_rcp_f32_e32 v157, v157
	v_rcp_f32_e32 v158, v161
	v_rcp_f32_e32 v160, v162
	v_rcp_f32_e32 v159, v163
	v_rcp_f32_e32 v161, v145
	s_waitcnt vmcnt(1)
	v_lshlrev_b32_e32 v162, 16, v176
	v_and_b32_e32 v163, 0xffff0000, v176
	v_lshlrev_b32_e32 v170, 16, v178
	v_and_b32_e32 v171, 0xffff0000, v178
	v_lshlrev_b32_e32 v166, 16, v177
	v_and_b32_e32 v167, 0xffff0000, v177
	v_lshlrev_b32_e32 v168, 16, v179
	v_and_b32_e32 v169, 0xffff0000, v179
	v_pk_mul_f32 v[154:155], v[154:155], v[162:163]
	v_pk_mul_f32 v[156:157], v[156:157], v[170:171]
	v_pk_mul_f32 v[158:159], v[158:159], v[166:167]
	v_pk_mul_f32 v[160:161], v[160:161], v[168:169]
	v_pk_mul_f32 v[126:127], v[126:127], v[154:155]
	v_pk_mul_f32 v[122:123], v[122:123], v[156:157]
	v_pk_mul_f32 v[128:129], v[128:129], v[158:159]
	v_pk_mul_f32 v[124:125], v[124:125], v[160:161]

.LBB0_853:
	v_add_u32_e32 v148, 16, v144
	v_ashrrev_i32_e32 v149, 31, v148
	v_lshlrev_b64 v[146:147], 13, v[148:149]
	v_lshl_add_u64 v[146:147], s[70:71], 0, v[146:147]
	v_lshl_add_u64 v[146:147], v[142:143], 1, v[146:147]
	v_lshl_add_u64 v[188:189], v[146:147], 0, s[12:13]
	global_load_dwordx4 v[172:175], v[188:189], off
	global_load_dwordx4 v[180:183], v[188:189], off offset:256
	s_cmp_lg_u32 s44, 3
	s_cbranch_scc1 .Lp5_noga_1
	global_load_dwordx4 v[176:179], v[146:147], off
	global_load_dwordx4 v[184:187], v[146:147], off offset:256
.Lp5_noga_1:
	v_add_co_u32_e32 v154, vcc, 0x1000, v146
	v_lshlrev_b64 v[148:149], 12, v[148:149]
	s_nop 0
	v_addc_co_u32_e32 v155, vcc, 0, v147, vcc
	v_lshl_add_u64 v[148:149], s[82:83], 0, v[148:149]
	s_mov_b64 s[20:21], -1
	s_and_b64 vcc, exec, s[4:5]
	v_lshl_add_u64 v[148:149], v[142:143], 1, v[148:149]
	s_waitcnt vmcnt(1)
	v_lshlrev_b32_e32 v159, 16, v172
	v_and_b32_e32 v158, 0xffff0000, v172
	v_lshlrev_b32_e32 v155, 16, v173
	v_and_b32_e32 v154, 0xffff0000, v173
	v_lshlrev_b32_e32 v160, 16, v174
	v_and_b32_e32 v157, 0xffff0000, v174
	v_lshlrev_b32_e32 v156, 16, v175
	v_and_b32_e32 v145, 0xffff0000, v175
	s_cbranch_vccnz .LBB0_855
	v_mul_f32_e32 v161, v118, v159
	v_mul_f32_e32 v162, v119, v158
	v_cvt_pk_bf16_f32 v166, v161, v162
	v_mul_f32_e32 v161, v120, v155
	v_mul_f32_e32 v162, v121, v154
	v_cvt_pk_bf16_f32 v167, v161, v162
	v_mul_f32_e32 v161, v114, v160
	v_mul_f32_e32 v162, v115, v157
	s_mov_b64 s[20:21], 0
	v_cvt_pk_bf16_f32 v168, v161, v162
	v_mul_f32_e32 v161, v116, v156
	v_mul_f32_e32 v162, v117, v145
	v_cvt_pk_bf16_f32 v169, v161, v162
	global_store_dwordx4 v[148:149], v[166:169], off
.LBB0_855:
	s_andn2_b64 vcc, exec, s[20:21]
	s_cbranch_vccnz .LBB0_857
	v_max_f32_e32 v159, v159, v159
	v_max_f32_e32 v160, v160, v160
	v_max_f32_e32 v158, v158, v158
	v_max_f32_e32 v157, v157, v157
	v_max_f32_e32 v155, v155, v155
	v_max_f32_e32 v156, v156, v156
	v_max_f32_e32 v154, v154, v154
	v_max_f32_e32 v145, v145, v145
	v_max_f32_e32 v159, 0xda24260, v159
	v_max_f32_e32 v160, 0xda24260, v160
	v_max_f32_e32 v158, 0xda24260, v158
	v_max_f32_e32 v157, 0xda24260, v157
	v_max_f32_e32 v161, 0xda24260, v155
	v_max_f32_e32 v162, 0xda24260, v156
	v_max_f32_e32 v163, 0xda24260, v154
	v_max_f32_e32 v145, 0xda24260, v145
	v_rcp_f32_e32 v154, v159
	v_rcp_f32_e32 v156, v160
	v_rcp_f32_e32 v155, v158
	v_rcp_f32_e32 v157, v157
	v_rcp_f32_e32 v158, v161
	v_rcp_f32_e32 v160, v162
	v_rcp_f32_e32 v159, v163
	v_rcp_f32_e32 v161, v145
	s_waitcnt vmcnt(1)
	v_lshlrev_b32_e32 v162, 16, v176
	v_and_b32_e32 v163, 0xffff0000, v176
	v_lshlrev_b32_e32 v170, 16, v178
	v_and_b32_e32 v171, 0xffff0000, v178
	v_lshlrev_b32_e32 v166, 16, v177
	v_and_b32_e32 v167, 0xffff0000, v177
	v_lshlrev_b32_e32 v168, 16, v179
	v_and_b32_e32 v169, 0xffff0000, v179
	v_pk_mul_f32 v[154:155], v[154:155], v[162:163]
	v_pk_mul_f32 v[156:157], v[156:157], v[170:171]
	v_pk_mul_f32 v[158:159], v[158:159], v[166:167]
	v_pk_mul_f32 v[160:161], v[160:161], v[168:169]
	v_pk_mul_f32 v[118:119], v[118:119], v[154:155]
	v_pk_mul_f32 v[114:115], v[114:115], v[156:157]
	v_pk_mul_f32 v[120:121], v[120:121], v[158:159]
	v_pk_mul_f32 v[116:117], v[116:117], v[160:161]

.LBB0_861:
	v_add_u32_e32 v148, 32, v144
	v_ashrrev_i32_e32 v149, 31, v148
	v_lshlrev_b64 v[146:147], 13, v[148:149]
	v_lshl_add_u64 v[146:147], s[70:71], 0, v[146:147]
	v_lshl_add_u64 v[146:147], v[142:143], 1, v[146:147]
	v_lshl_add_u64 v[188:189], v[146:147], 0, s[12:13]
	global_load_dwordx4 v[172:175], v[188:189], off
	global_load_dwordx4 v[180:183], v[188:189], off offset:256
	s_cmp_lg_u32 s44, 3
	s_cbranch_scc1 .Lp5_noga_2
	global_load_dwordx4 v[176:179], v[146:147], off
	global_load_dwordx4 v[184:187], v[146:147], off offset:256
.Lp5_noga_2:
	v_add_co_u32_e32 v154, vcc, 0x1000, v146
	v_lshlrev_b64 v[148:149], 12, v[148:149]
	s_nop 0
	v_addc_co_u32_e32 v155, vcc, 0, v147, vcc
	v_lshl_add_u64 v[148:149], s[82:83], 0, v[148:149]
	s_mov_b64 s[20:21], -1
	s_and_b64 vcc, exec, s[4:5]
	v_lshl_add_u64 v[148:149], v[142:143], 1, v[148:149]
	s_waitcnt vmcnt(1)
	v_lshlrev_b32_e32 v159, 16, v172
	v_and_b32_e32 v158, 0xffff0000, v172
	v_lshlrev_b32_e32 v155, 16, v173
	v_and_b32_e32 v154, 0xffff0000, v173
	v_lshlrev_b32_e32 v160, 16, v174
	v_and_b32_e32 v157, 0xffff0000, v174
	v_lshlrev_b32_e32 v156, 16, v175
	v_and_b32_e32 v145, 0xffff0000, v175
	s_cbranch_vccnz .LBB0_863
	v_mul_f32_e32 v161, v110, v159
	v_mul_f32_e32 v162, v111, v158
	v_cvt_pk_bf16_f32 v166, v161, v162
	v_mul_f32_e32 v161, v112, v155
	v_mul_f32_e32 v162, v113, v154
	v_cvt_pk_bf16_f32 v167, v161, v162
	v_mul_f32_e32 v161, v106, v160
	v_mul_f32_e32 v162, v107, v157
	s_mov_b64 s[20:21], 0
	v_cvt_pk_bf16_f32 v168, v161, v162
	v_mul_f32_e32 v161, v108, v156
	v_mul_f32_e32 v162, v109, v145
	v_cvt_pk_bf16_f32 v169, v161, v162
	global_store_dwordx4 v[148:149], v[166:169], off
.LBB0_863:
	s_andn2_b64 vcc, exec, s[20:21]
	s_cbranch_vccnz .LBB0_865
	v_max_f32_e32 v159, v159, v159
	v_max_f32_e32 v160, v160, v160
	v_max_f32_e32 v158, v158, v158
	v_max_f32_e32 v157, v157, v157
	v_max_f32_e32 v155, v155, v155
	v_max_f32_e32 v156, v156, v156
	v_max_f32_e32 v154, v154, v154
	v_max_f32_e32 v145, v145, v145
	v_max_f32_e32 v159, 0xda24260, v159
	v_max_f32_e32 v160, 0xda24260, v160
	v_max_f32_e32 v158, 0xda24260, v158
	v_max_f32_e32 v157, 0xda24260, v157
	v_max_f32_e32 v161, 0xda24260, v155
	v_max_f32_e32 v162, 0xda24260, v156
	v_max_f32_e32 v163, 0xda24260, v154
	v_max_f32_e32 v145, 0xda24260, v145
	v_rcp_f32_e32 v154, v159
	v_rcp_f32_e32 v156, v160
	v_rcp_f32_e32 v155, v158
	v_rcp_f32_e32 v157, v157
	v_rcp_f32_e32 v158, v161
	v_rcp_f32_e32 v160, v162
	v_rcp_f32_e32 v159, v163
	v_rcp_f32_e32 v161, v145
	s_waitcnt vmcnt(1)
	v_lshlrev_b32_e32 v162, 16, v176
	v_and_b32_e32 v163, 0xffff0000, v176
	v_lshlrev_b32_e32 v170, 16, v178
	v_and_b32_e32 v171, 0xffff0000, v178
	v_lshlrev_b32_e32 v166, 16, v177
	v_and_b32_e32 v167, 0xffff0000, v177
	v_lshlrev_b32_e32 v168, 16, v179
	v_and_b32_e32 v169, 0xffff0000, v179
	v_pk_mul_f32 v[154:155], v[154:155], v[162:163]
	v_pk_mul_f32 v[156:157], v[156:157], v[170:171]
	v_pk_mul_f32 v[158:159], v[158:159], v[166:167]
	v_pk_mul_f32 v[160:161], v[160:161], v[168:169]
	v_pk_mul_f32 v[110:111], v[110:111], v[154:155]
	v_pk_mul_f32 v[106:107], v[106:107], v[156:157]
	v_pk_mul_f32 v[112:113], v[112:113], v[158:159]
	v_pk_mul_f32 v[108:109], v[108:109], v[160:161]

.LBB0_869:
	v_add_u32_e32 v148, 48, v144
	v_ashrrev_i32_e32 v149, 31, v148
	v_lshlrev_b64 v[146:147], 13, v[148:149]
	v_lshl_add_u64 v[146:147], s[70:71], 0, v[146:147]
	v_lshl_add_u64 v[146:147], v[142:143], 1, v[146:147]
	v_lshl_add_u64 v[188:189], v[146:147], 0, s[12:13]
	global_load_dwordx4 v[172:175], v[188:189], off
	global_load_dwordx4 v[180:183], v[188:189], off offset:256
	s_cmp_lg_u32 s44, 3
	s_cbranch_scc1 .Lp5_noga_3
	global_load_dwordx4 v[176:179], v[146:147], off
	global_load_dwordx4 v[184:187], v[146:147], off offset:256
.Lp5_noga_3:
	v_add_co_u32_e32 v154, vcc, 0x1000, v146
	v_lshlrev_b64 v[148:149], 12, v[148:149]
	s_nop 0
	v_addc_co_u32_e32 v155, vcc, 0, v147, vcc
	v_lshl_add_u64 v[148:149], s[82:83], 0, v[148:149]
	s_mov_b64 s[20:21], -1
	s_and_b64 vcc, exec, s[4:5]
	v_lshl_add_u64 v[148:149], v[142:143], 1, v[148:149]
	s_waitcnt vmcnt(1)
	v_lshlrev_b32_e32 v159, 16, v172
	v_and_b32_e32 v158, 0xffff0000, v172
	v_lshlrev_b32_e32 v155, 16, v173
	v_and_b32_e32 v154, 0xffff0000, v173
	v_lshlrev_b32_e32 v160, 16, v174
	v_and_b32_e32 v157, 0xffff0000, v174
	v_lshlrev_b32_e32 v156, 16, v175
	v_and_b32_e32 v145, 0xffff0000, v175
	s_cbranch_vccnz .LBB0_871
	v_mul_f32_e32 v161, v102, v159
	v_mul_f32_e32 v162, v103, v158
	v_cvt_pk_bf16_f32 v166, v161, v162
	v_mul_f32_e32 v161, v104, v155
	v_mul_f32_e32 v162, v105, v154
	v_cvt_pk_bf16_f32 v167, v161, v162
	v_mul_f32_e32 v161, v98, v160
	v_mul_f32_e32 v162, v99, v157
	s_mov_b64 s[20:21], 0
	v_cvt_pk_bf16_f32 v168, v161, v162
	v_mul_f32_e32 v161, v100, v156
	v_mul_f32_e32 v162, v101, v145
	v_cvt_pk_bf16_f32 v169, v161, v162
	global_store_dwordx4 v[148:149], v[166:169], off
.LBB0_871:
	s_andn2_b64 vcc, exec, s[20:21]
	s_cbranch_vccnz .LBB0_873
	v_max_f32_e32 v159, v159, v159
	v_max_f32_e32 v160, v160, v160
	v_max_f32_e32 v158, v158, v158
	v_max_f32_e32 v157, v157, v157
	v_max_f32_e32 v155, v155, v155
	v_max_f32_e32 v156, v156, v156
	v_max_f32_e32 v154, v154, v154
	v_max_f32_e32 v145, v145, v145
	v_max_f32_e32 v159, 0xda24260, v159
	v_max_f32_e32 v160, 0xda24260, v160
	v_max_f32_e32 v158, 0xda24260, v158
	v_max_f32_e32 v157, 0xda24260, v157
	v_max_f32_e32 v161, 0xda24260, v155
	v_max_f32_e32 v162, 0xda24260, v156
	v_max_f32_e32 v163, 0xda24260, v154
	v_max_f32_e32 v145, 0xda24260, v145
	v_rcp_f32_e32 v154, v159
	v_rcp_f32_e32 v156, v160
	v_rcp_f32_e32 v155, v158
	v_rcp_f32_e32 v157, v157
	v_rcp_f32_e32 v158, v161
	v_rcp_f32_e32 v160, v162
	v_rcp_f32_e32 v159, v163
	v_rcp_f32_e32 v161, v145
	s_waitcnt vmcnt(1)
	v_lshlrev_b32_e32 v162, 16, v176
	v_and_b32_e32 v163, 0xffff0000, v176
	v_lshlrev_b32_e32 v170, 16, v178
	v_and_b32_e32 v171, 0xffff0000, v178
	v_lshlrev_b32_e32 v166, 16, v177
	v_and_b32_e32 v167, 0xffff0000, v177
	v_lshlrev_b32_e32 v168, 16, v179
	v_and_b32_e32 v169, 0xffff0000, v179
	v_pk_mul_f32 v[154:155], v[154:155], v[162:163]
	v_pk_mul_f32 v[156:157], v[156:157], v[170:171]
	v_pk_mul_f32 v[158:159], v[158:159], v[166:167]
	v_pk_mul_f32 v[160:161], v[160:161], v[168:169]
	v_pk_mul_f32 v[102:103], v[102:103], v[154:155]
	v_pk_mul_f32 v[98:99], v[98:99], v[156:157]
	v_pk_mul_f32 v[104:105], v[104:105], v[158:159]
	v_pk_mul_f32 v[100:101], v[100:101], v[160:161]

.LBB0_877:
	v_add_u32_e32 v148, 0x80, v144
	v_ashrrev_i32_e32 v149, 31, v148
	v_lshlrev_b64 v[146:147], 13, v[148:149]
	v_lshl_add_u64 v[146:147], s[70:71], 0, v[146:147]
	v_lshl_add_u64 v[146:147], v[142:143], 1, v[146:147]
	v_lshl_add_u64 v[188:189], v[146:147], 0, s[12:13]
	global_load_dwordx4 v[172:175], v[188:189], off
	global_load_dwordx4 v[180:183], v[188:189], off offset:256
	s_cmp_lg_u32 s44, 3
	s_cbranch_scc1 .Lp5_noga_4
	global_load_dwordx4 v[176:179], v[146:147], off
	global_load_dwordx4 v[184:187], v[146:147], off offset:256
.Lp5_noga_4:
	v_add_co_u32_e32 v154, vcc, 0x1000, v146
	v_lshlrev_b64 v[148:149], 12, v[148:149]
	s_nop 0
	v_addc_co_u32_e32 v155, vcc, 0, v147, vcc
	v_lshl_add_u64 v[148:149], s[82:83], 0, v[148:149]
	s_mov_b64 s[20:21], -1
	s_and_b64 vcc, exec, s[4:5]
	v_lshl_add_u64 v[148:149], v[142:143], 1, v[148:149]
	s_waitcnt vmcnt(1)
	v_lshlrev_b32_e32 v159, 16, v172
	v_and_b32_e32 v158, 0xffff0000, v172
	v_lshlrev_b32_e32 v155, 16, v173
	v_and_b32_e32 v154, 0xffff0000, v173
	v_lshlrev_b32_e32 v160, 16, v174
	v_and_b32_e32 v157, 0xffff0000, v174
	v_lshlrev_b32_e32 v156, 16, v175
	v_and_b32_e32 v145, 0xffff0000, v175
	s_cbranch_vccnz .LBB0_879
	v_mul_f32_e32 v161, v62, v159
	v_mul_f32_e32 v162, v63, v158
	v_cvt_pk_bf16_f32 v166, v161, v162
	v_mul_f32_e32 v161, v64, v155
	v_mul_f32_e32 v162, v65, v154
	v_cvt_pk_bf16_f32 v167, v161, v162
	v_mul_f32_e32 v161, v58, v160
	v_mul_f32_e32 v162, v59, v157
	s_mov_b64 s[20:21], 0
	v_cvt_pk_bf16_f32 v168, v161, v162
	v_mul_f32_e32 v161, v60, v156
	v_mul_f32_e32 v162, v61, v145
	v_cvt_pk_bf16_f32 v169, v161, v162
	global_store_dwordx4 v[148:149], v[166:169], off
.LBB0_879:
	s_andn2_b64 vcc, exec, s[20:21]
	s_cbranch_vccnz .LBB0_881
	v_max_f32_e32 v159, v159, v159
	v_max_f32_e32 v160, v160, v160
	v_max_f32_e32 v158, v158, v158
	v_max_f32_e32 v157, v157, v157
	v_max_f32_e32 v155, v155, v155
	v_max_f32_e32 v156, v156, v156
	v_max_f32_e32 v154, v154, v154
	v_max_f32_e32 v145, v145, v145
	v_max_f32_e32 v159, 0xda24260, v159
	v_max_f32_e32 v160, 0xda24260, v160
	v_max_f32_e32 v158, 0xda24260, v158
	v_max_f32_e32 v157, 0xda24260, v157
	v_max_f32_e32 v161, 0xda24260, v155
	v_max_f32_e32 v162, 0xda24260, v156
	v_max_f32_e32 v163, 0xda24260, v154
	v_max_f32_e32 v145, 0xda24260, v145
	v_rcp_f32_e32 v154, v159
	v_rcp_f32_e32 v156, v160
	v_rcp_f32_e32 v155, v158
	v_rcp_f32_e32 v157, v157
	v_rcp_f32_e32 v158, v161
	v_rcp_f32_e32 v160, v162
	v_rcp_f32_e32 v159, v163
	v_rcp_f32_e32 v161, v145
	s_waitcnt vmcnt(1)
	v_lshlrev_b32_e32 v162, 16, v176
	v_and_b32_e32 v163, 0xffff0000, v176
	v_lshlrev_b32_e32 v170, 16, v178
	v_and_b32_e32 v171, 0xffff0000, v178
	v_lshlrev_b32_e32 v166, 16, v177
	v_and_b32_e32 v167, 0xffff0000, v177
	v_lshlrev_b32_e32 v168, 16, v179
	v_and_b32_e32 v169, 0xffff0000, v179
	v_pk_mul_f32 v[154:155], v[154:155], v[162:163]
	v_pk_mul_f32 v[156:157], v[156:157], v[170:171]
	v_pk_mul_f32 v[158:159], v[158:159], v[166:167]
	v_pk_mul_f32 v[160:161], v[160:161], v[168:169]
	v_pk_mul_f32 v[62:63], v[62:63], v[154:155]
	v_pk_mul_f32 v[58:59], v[58:59], v[156:157]
	v_pk_mul_f32 v[64:65], v[64:65], v[158:159]
	v_pk_mul_f32 v[60:61], v[60:61], v[160:161]

.LBB0_885:
	v_add_u32_e32 v148, 0x90, v144
	v_ashrrev_i32_e32 v149, 31, v148
	v_lshlrev_b64 v[146:147], 13, v[148:149]
	v_lshl_add_u64 v[146:147], s[70:71], 0, v[146:147]
	v_lshl_add_u64 v[146:147], v[142:143], 1, v[146:147]
	v_lshl_add_u64 v[188:189], v[146:147], 0, s[12:13]
	global_load_dwordx4 v[172:175], v[188:189], off
	global_load_dwordx4 v[180:183], v[188:189], off offset:256
	s_cmp_lg_u32 s44, 3
	s_cbranch_scc1 .Lp5_noga_5
	global_load_dwordx4 v[176:179], v[146:147], off
	global_load_dwordx4 v[184:187], v[146:147], off offset:256
.Lp5_noga_5:
	v_add_co_u32_e32 v154, vcc, 0x1000, v146
	v_lshlrev_b64 v[148:149], 12, v[148:149]
	s_nop 0
	v_addc_co_u32_e32 v155, vcc, 0, v147, vcc
	v_lshl_add_u64 v[148:149], s[82:83], 0, v[148:149]
	s_mov_b64 s[20:21], -1
	s_and_b64 vcc, exec, s[4:5]
	v_lshl_add_u64 v[148:149], v[142:143], 1, v[148:149]
	s_waitcnt vmcnt(1)
	v_lshlrev_b32_e32 v159, 16, v172
	v_and_b32_e32 v158, 0xffff0000, v172
	v_lshlrev_b32_e32 v155, 16, v173
	v_and_b32_e32 v154, 0xffff0000, v173
	v_lshlrev_b32_e32 v160, 16, v174
	v_and_b32_e32 v157, 0xffff0000, v174
	v_lshlrev_b32_e32 v156, 16, v175
	v_and_b32_e32 v145, 0xffff0000, v175
	s_cbranch_vccnz .LBB0_887
	v_mul_f32_e32 v161, v54, v159
	v_mul_f32_e32 v162, v55, v158
	v_cvt_pk_bf16_f32 v166, v161, v162
	v_mul_f32_e32 v161, v56, v155
	v_mul_f32_e32 v162, v57, v154
	v_cvt_pk_bf16_f32 v167, v161, v162
	v_mul_f32_e32 v161, v50, v160
	v_mul_f32_e32 v162, v51, v157
	s_mov_b64 s[20:21], 0
	v_cvt_pk_bf16_f32 v168, v161, v162
	v_mul_f32_e32 v161, v52, v156
	v_mul_f32_e32 v162, v53, v145
	v_cvt_pk_bf16_f32 v169, v161, v162
	global_store_dwordx4 v[148:149], v[166:169], off
.LBB0_887:
	s_andn2_b64 vcc, exec, s[20:21]
	s_cbranch_vccnz .LBB0_889
	v_max_f32_e32 v159, v159, v159
	v_max_f32_e32 v160, v160, v160
	v_max_f32_e32 v158, v158, v158
	v_max_f32_e32 v157, v157, v157
	v_max_f32_e32 v155, v155, v155
	v_max_f32_e32 v156, v156, v156
	v_max_f32_e32 v154, v154, v154
	v_max_f32_e32 v145, v145, v145
	v_max_f32_e32 v159, 0xda24260, v159
	v_max_f32_e32 v160, 0xda24260, v160
	v_max_f32_e32 v158, 0xda24260, v158
	v_max_f32_e32 v157, 0xda24260, v157
	v_max_f32_e32 v161, 0xda24260, v155
	v_max_f32_e32 v162, 0xda24260, v156
	v_max_f32_e32 v163, 0xda24260, v154
	v_max_f32_e32 v145, 0xda24260, v145
	v_rcp_f32_e32 v154, v159
	v_rcp_f32_e32 v156, v160
	v_rcp_f32_e32 v155, v158
	v_rcp_f32_e32 v157, v157
	v_rcp_f32_e32 v158, v161
	v_rcp_f32_e32 v160, v162
	v_rcp_f32_e32 v159, v163
	v_rcp_f32_e32 v161, v145
	s_waitcnt vmcnt(1)
	v_lshlrev_b32_e32 v162, 16, v176
	v_and_b32_e32 v163, 0xffff0000, v176
	v_lshlrev_b32_e32 v170, 16, v178
	v_and_b32_e32 v171, 0xffff0000, v178
	v_lshlrev_b32_e32 v166, 16, v177
	v_and_b32_e32 v167, 0xffff0000, v177
	v_lshlrev_b32_e32 v168, 16, v179
	v_and_b32_e32 v169, 0xffff0000, v179
	v_pk_mul_f32 v[154:155], v[154:155], v[162:163]
	v_pk_mul_f32 v[156:157], v[156:157], v[170:171]
	v_pk_mul_f32 v[158:159], v[158:159], v[166:167]
	v_pk_mul_f32 v[160:161], v[160:161], v[168:169]
	v_pk_mul_f32 v[54:55], v[54:55], v[154:155]
	v_pk_mul_f32 v[50:51], v[50:51], v[156:157]
	v_pk_mul_f32 v[56:57], v[56:57], v[158:159]
	v_pk_mul_f32 v[52:53], v[52:53], v[160:161]

.LBB0_893:
	v_add_u32_e32 v148, 0xa0, v144
	v_ashrrev_i32_e32 v149, 31, v148
	v_lshlrev_b64 v[146:147], 13, v[148:149]
	v_lshl_add_u64 v[146:147], s[70:71], 0, v[146:147]
	v_lshl_add_u64 v[146:147], v[142:143], 1, v[146:147]
	v_lshl_add_u64 v[188:189], v[146:147], 0, s[12:13]
	global_load_dwordx4 v[172:175], v[188:189], off
	global_load_dwordx4 v[180:183], v[188:189], off offset:256
	s_cmp_lg_u32 s44, 3
	s_cbranch_scc1 .Lp5_noga_6
	global_load_dwordx4 v[176:179], v[146:147], off
	global_load_dwordx4 v[184:187], v[146:147], off offset:256
.Lp5_noga_6:
	v_add_co_u32_e32 v154, vcc, 0x1000, v146
	v_lshlrev_b64 v[148:149], 12, v[148:149]
	s_nop 0
	v_addc_co_u32_e32 v155, vcc, 0, v147, vcc
	v_lshl_add_u64 v[148:149], s[82:83], 0, v[148:149]
	s_mov_b64 s[20:21], -1
	s_and_b64 vcc, exec, s[4:5]
	v_lshl_add_u64 v[148:149], v[142:143], 1, v[148:149]
	s_waitcnt vmcnt(1)
	v_lshlrev_b32_e32 v159, 16, v172
	v_and_b32_e32 v158, 0xffff0000, v172
	v_lshlrev_b32_e32 v155, 16, v173
	v_and_b32_e32 v154, 0xffff0000, v173
	v_lshlrev_b32_e32 v160, 16, v174
	v_and_b32_e32 v157, 0xffff0000, v174
	v_lshlrev_b32_e32 v156, 16, v175
	v_and_b32_e32 v145, 0xffff0000, v175
	s_cbranch_vccnz .LBB0_895
	v_mul_f32_e32 v161, v46, v159
	v_mul_f32_e32 v162, v47, v158
	v_cvt_pk_bf16_f32 v166, v161, v162
	v_mul_f32_e32 v161, v48, v155
	v_mul_f32_e32 v162, v49, v154
	v_cvt_pk_bf16_f32 v167, v161, v162
	v_mul_f32_e32 v161, v42, v160
	v_mul_f32_e32 v162, v43, v157
	s_mov_b64 s[20:21], 0
	v_cvt_pk_bf16_f32 v168, v161, v162
	v_mul_f32_e32 v161, v44, v156
	v_mul_f32_e32 v162, v45, v145
	v_cvt_pk_bf16_f32 v169, v161, v162
	global_store_dwordx4 v[148:149], v[166:169], off
.LBB0_895:
	s_andn2_b64 vcc, exec, s[20:21]
	s_cbranch_vccnz .LBB0_897
	v_max_f32_e32 v159, v159, v159
	v_max_f32_e32 v160, v160, v160
	v_max_f32_e32 v158, v158, v158
	v_max_f32_e32 v157, v157, v157
	v_max_f32_e32 v155, v155, v155
	v_max_f32_e32 v156, v156, v156
	v_max_f32_e32 v154, v154, v154
	v_max_f32_e32 v145, v145, v145
	v_max_f32_e32 v159, 0xda24260, v159
	v_max_f32_e32 v160, 0xda24260, v160
	v_max_f32_e32 v158, 0xda24260, v158
	v_max_f32_e32 v157, 0xda24260, v157
	v_max_f32_e32 v161, 0xda24260, v155
	v_max_f32_e32 v162, 0xda24260, v156
	v_max_f32_e32 v163, 0xda24260, v154
	v_max_f32_e32 v145, 0xda24260, v145
	v_rcp_f32_e32 v154, v159
	v_rcp_f32_e32 v156, v160
	v_rcp_f32_e32 v155, v158
	v_rcp_f32_e32 v157, v157
	v_rcp_f32_e32 v158, v161
	v_rcp_f32_e32 v160, v162
	v_rcp_f32_e32 v159, v163
	v_rcp_f32_e32 v161, v145
	s_waitcnt vmcnt(1)
	v_lshlrev_b32_e32 v162, 16, v176
	v_and_b32_e32 v163, 0xffff0000, v176
	v_lshlrev_b32_e32 v170, 16, v178
	v_and_b32_e32 v171, 0xffff0000, v178
	v_lshlrev_b32_e32 v166, 16, v177
	v_and_b32_e32 v167, 0xffff0000, v177
	v_lshlrev_b32_e32 v168, 16, v179
	v_and_b32_e32 v169, 0xffff0000, v179
	v_pk_mul_f32 v[154:155], v[154:155], v[162:163]
	v_pk_mul_f32 v[156:157], v[156:157], v[170:171]
	v_pk_mul_f32 v[158:159], v[158:159], v[166:167]
	v_pk_mul_f32 v[160:161], v[160:161], v[168:169]
	v_pk_mul_f32 v[46:47], v[46:47], v[154:155]
	v_pk_mul_f32 v[42:43], v[42:43], v[156:157]
	v_pk_mul_f32 v[48:49], v[48:49], v[158:159]
	v_pk_mul_f32 v[44:45], v[44:45], v[160:161]
